# s5_pass2 scan: B.u of the 32 steps of a sub-block on the f32 matrix core (v_mfma_f32_32x32x2_f32, f32 operands and accumulate, k-ordered fma chain), recurrence stays on the VALU
# speedup vs baseline: 1.0004x; 1.0004x over previous
; __device__ __forceinline__ void s5_pass2(const Params& p, int layer, int task, char* sm) {
;     ...
;     const int g = w * 8 + gi;
;     const size_t pi = ((size_t)(layer * 32 + g)) * 64 + lane;
;     f32x2 B2[16];
; #pragma unroll
;     for (int h = 0; h < 16; h++) { B2[h].x = p.SB[pi * 32 + h]; B2[h].y = p.SB[pi * 32 + 16 + h]; }
;     const float ar = p.SA[pi * 4], ai = p.SA[pi * 4 + 1];
;     float2 s0 = *(const float2*)(p.END + (((size_t)(b * 128 + c) * 32 + g) * 64 + lane) * 2);
;     float sr = s0.x, si = s0.y;
;     bf16x8 cf[4];
;     {
;       const bf* cm = p.CM + (((size_t)(layer * 32 + g)) * 16 + (lane & 15)) * 128 + 8 * (lane >> 4);
; #pragma unroll
;       for (int ks = 0; ks < 4; ks++) cf[ks] = *(const bf16x8*)(cm + ks * 32);
;     }
;     const float dsk = p.s5_d[(layer * 32 + g) * 16 + (lane & 15)];
.LBB0_1790:
	v_add_u32_e32 v101, s10, v80
	v_add_u32_e32 v144, s35, v101
	v_lshlrev_b64 v[40:41], 6, v[144:145]
	v_or_b32_e32 v40, v40, v44
	v_readlane_b32 s12, v253, 38
	v_lshlrev_b64 v[8:9], 7, v[40:41]
	v_readlane_b32 s16, v253, 42
	v_readlane_b32 s17, v253, 43
	v_readlane_b32 s18, v253, 44
	v_readlane_b32 s19, v253, 45
	v_lshl_add_u64 v[20:21], s[16:17], 0, v[8:9]
	global_load_dwordx4 v[24:27], v[20:21], off offset:48
	global_load_dwordx4 v[28:31], v[20:21], off offset:32
	global_load_dwordx4 v[32:35], v[20:21], off offset:16
	global_load_dwordx4 v[36:39], v[20:21], off
	global_load_dwordx4 v[8:11], v[20:21], off offset:112
	global_load_dwordx4 v[12:15], v[20:21], off offset:96
	global_load_dwordx4 v[16:19], v[20:21], off offset:80
	s_nop 0
	global_load_dwordx4 v[20:23], v[20:21], off offset:64
	v_readlane_b32 s13, v253, 39
	v_readlane_b32 s14, v253, 40
	v_readlane_b32 s15, v253, 41
	s_cmp_lg_u32 s10, 7
	s_cselect_b64 s[6:7], -1, 0
	s_xor_b64 s[6:7], s[6:7], -1
	s_mov_b32 s11, 0
	s_waitcnt vmcnt(7)
	v_mov_b32_e32 v64, v24
	v_mov_b32_e32 v66, v26
	v_lshl_or_b32 v26, v101, 6, v50
	s_waitcnt vmcnt(4)
	v_mov_b32_e32 v52, v36
	s_waitcnt vmcnt(3)
	v_mov_b32_e32 v65, v8
	v_mov_b32_e32 v8, v25
	v_mov_b32_e32 v67, v10
	v_mov_b32_e32 v10, v27
	v_lshl_add_u64 v[24:25], v[40:41], 4, s[18:19]
	v_mov_b32_e32 v27, v45
	v_lshl_add_u64 v[26:27], v[26:27], 3, s[12:13]
	global_load_dwordx2 v[68:69], v[24:25], off
	global_load_dwordx2 v[70:71], v[26:27], off
	v_lshlrev_b64 v[24:25], 12, v[144:145]
	s_waitcnt vmcnt(2)
	v_mov_b32_e32 v53, v20
	v_mov_b32_e32 v20, v37
	v_lshl_add_u64 v[36:37], v[46:47], 0, v[24:25]
	v_readlane_b32 s12, v252, 16
	v_mov_b32_e32 v54, v38
	v_mov_b32_e32 v55, v22
	v_mov_b32_e32 v22, v39
	v_mov_b32_e32 v56, v32
	v_mov_b32_e32 v57, v16
	v_mov_b32_e32 v16, v33
	v_mov_b32_e32 v58, v34
	v_mov_b32_e32 v59, v18
	v_mov_b32_e32 v18, v35
	v_mov_b32_e32 v60, v28
	v_mov_b32_e32 v61, v12
	v_mov_b32_e32 v12, v29
	v_mov_b32_e32 v62, v30
	v_mov_b32_e32 v63, v14
	v_mov_b32_e32 v14, v31
	global_load_dwordx4 v[24:27], v[36:37], off
	global_load_dwordx4 v[28:31], v[36:37], off offset:64
	global_load_dwordx4 v[32:35], v[36:37], off offset:128
	s_nop 0
	global_load_dwordx4 v[36:39], v[36:37], off offset:192
	v_lshl_or_b32 v144, v144, 4, v81
	v_readlane_b32 s20, v252, 24
	v_readlane_b32 s21, v252, 25
	v_readlane_b32 s13, v252, 17
	v_readlane_b32 s14, v252, 18
	v_lshl_add_u64 v[40:41], v[144:145], 2, s[20:21]
	global_load_dword v102, v[40:41], off
	v_lshlrev_b32_e32 v144, 5, v101
	v_lshl_add_u64 v[72:73], v[48:49], 0, v[144:145]
	v_readlane_b32 s15, v252, 19
	v_readlane_b32 s16, v252, 20
	v_readlane_b32 s17, v252, 21
	v_readlane_b32 s18, v252, 22
	v_readlane_b32 s19, v252, 23
	v_readlane_b32 s22, v252, 26
	v_readlane_b32 s23, v252, 27
	v_readlane_b32 s24, v252, 28
	v_readlane_b32 s25, v252, 29
	v_readlane_b32 s26, v252, 30
	v_readlane_b32 s27, v252, 31
	s_waitcnt vmcnt(6)
	v_pk_mov_b32 v[74:75], v[68:69], v[68:69] op_sel:[1,0]
	s_nop 1
	v_permlane32_swap_b32_e32 v52, v20
	v_permlane32_swap_b32_e32 v53, v21
	v_permlane32_swap_b32_e32 v54, v22
	v_permlane32_swap_b32_e32 v55, v23
	v_permlane32_swap_b32_e32 v56, v16
	v_permlane32_swap_b32_e32 v57, v17
	v_permlane32_swap_b32_e32 v58, v18
	v_permlane32_swap_b32_e32 v59, v19
	v_permlane32_swap_b32_e32 v60, v12
	v_permlane32_swap_b32_e32 v61, v13
	v_permlane32_swap_b32_e32 v62, v14
	v_permlane32_swap_b32_e32 v63, v15
	v_permlane32_swap_b32_e32 v64, v8
	v_permlane32_swap_b32_e32 v65, v9
	v_permlane32_swap_b32_e32 v66, v10
	v_permlane32_swap_b32_e32 v67, v11

; __device__ __forceinline__ bf f2bf(float f) { return (bf)(pk2(f, 0.f) & 0xFFFFu); }
; __device__ __forceinline__ void s5_pass2(const Params& p, int layer, int task, char* sm) {
;     ...
;     for (int sub = 0; sub < 4; sub++) {
;       __builtin_amdgcn_wave_barrier();
;       if (lane < 32) s5_st_u(sU + lane * 16, ua, ub);
;       {
;         const int nsub = (sub + 1) & 3; const int ng = g + (sub == 3 ? 1 : 0);
;         if (sub < 3 || gi < 7) s5_ld_u(p, tok0 + nsub * 32 + (lane & 31), ng, ua, ub);
;       }
;       __builtin_amdgcn_wave_barrier();
;       for (int l = 0; l < 32; l++) {
;         S5_STEP(sU + l * 16)
;         sS[l * 136 + lane] = f2bf(sr); sS[l * 136 + 64 + lane] = f2bf(si);
;       }
.LBB0_1796:
	v_add_u32_e32 v103, v79, v40
	v_and_b32_e32 v43, 31, v202
	v_lshrrev_b32_e32 v42, 5, v202
	v_lshlrev_b32_e32 v43, 6, v43
	v_lshl_add_u32 v43, v42, 2, v43
	v_add_u32_e32 v43, v79, v43
	ds_read2_b32 v[170:171], v43 offset0:0 offset1:2
	ds_read2_b32 v[172:173], v43 offset0:4 offset1:6
	ds_read2_b32 v[174:175], v43 offset0:8 offset1:10
	ds_read2_b32 v[176:177], v43 offset0:12 offset1:14
	s_waitcnt lgkmcnt(0)
	v_mfma_f32_32x32x2_f32 v[104:119], v170, v52, 0
	v_mfma_f32_32x32x2_f32 v[120:135], v170, v53, 0
	v_mfma_f32_32x32x2_f32 v[152:167], v170, v20, 0
	v_mfma_f32_32x32x2_f32 v[136:151], v170, v21, 0
	v_mfma_f32_32x32x2_f32 v[104:119], v171, v54, v[104:119]
	v_mfma_f32_32x32x2_f32 v[120:135], v171, v55, v[120:135]
	v_mfma_f32_32x32x2_f32 v[152:167], v171, v22, v[152:167]
	v_mfma_f32_32x32x2_f32 v[136:151], v171, v23, v[136:151]
	v_mfma_f32_32x32x2_f32 v[104:119], v172, v56, v[104:119]
	v_mfma_f32_32x32x2_f32 v[120:135], v172, v57, v[120:135]
	v_mfma_f32_32x32x2_f32 v[152:167], v172, v16, v[152:167]
	v_mfma_f32_32x32x2_f32 v[136:151], v172, v17, v[136:151]
	v_mfma_f32_32x32x2_f32 v[104:119], v173, v58, v[104:119]
	v_mfma_f32_32x32x2_f32 v[120:135], v173, v59, v[120:135]
	v_mfma_f32_32x32x2_f32 v[152:167], v173, v18, v[152:167]
	v_mfma_f32_32x32x2_f32 v[136:151], v173, v19, v[136:151]
	v_mfma_f32_32x32x2_f32 v[104:119], v174, v60, v[104:119]
	v_mfma_f32_32x32x2_f32 v[120:135], v174, v61, v[120:135]
	v_mfma_f32_32x32x2_f32 v[152:167], v174, v12, v[152:167]
	v_mfma_f32_32x32x2_f32 v[136:151], v174, v13, v[136:151]
	v_mfma_f32_32x32x2_f32 v[104:119], v175, v62, v[104:119]
	v_mfma_f32_32x32x2_f32 v[120:135], v175, v63, v[120:135]
	v_mfma_f32_32x32x2_f32 v[152:167], v175, v14, v[152:167]
	v_mfma_f32_32x32x2_f32 v[136:151], v175, v15, v[136:151]
	v_mfma_f32_32x32x2_f32 v[104:119], v176, v64, v[104:119]
	v_mfma_f32_32x32x2_f32 v[120:135], v176, v65, v[120:135]
	v_mfma_f32_32x32x2_f32 v[152:167], v176, v8, v[152:167]
	v_mfma_f32_32x32x2_f32 v[136:151], v176, v9, v[136:151]
	v_mfma_f32_32x32x2_f32 v[104:119], v177, v66, v[104:119]
	v_mfma_f32_32x32x2_f32 v[120:135], v177, v67, v[120:135]
	v_mfma_f32_32x32x2_f32 v[152:167], v177, v10, v[152:167]
	v_mfma_f32_32x32x2_f32 v[136:151], v177, v11, v[136:151]
	s_nop 7
	s_nop 7
	s_nop 7
	v_permlane32_swap_b32_e32 v104, v152
	v_permlane32_swap_b32_e32 v120, v136
	v_permlane32_swap_b32_e32 v105, v153
	v_permlane32_swap_b32_e32 v121, v137
	v_permlane32_swap_b32_e32 v106, v154
	v_permlane32_swap_b32_e32 v122, v138
	v_permlane32_swap_b32_e32 v107, v155
	v_permlane32_swap_b32_e32 v123, v139
	v_permlane32_swap_b32_e32 v108, v156
	v_permlane32_swap_b32_e32 v124, v140
	v_permlane32_swap_b32_e32 v109, v157
	v_permlane32_swap_b32_e32 v125, v141
	v_permlane32_swap_b32_e32 v110, v158
	v_permlane32_swap_b32_e32 v126, v142
	v_permlane32_swap_b32_e32 v111, v159
	v_permlane32_swap_b32_e32 v127, v143
	v_permlane32_swap_b32_e32 v112, v160
	v_permlane32_swap_b32_e32 v128, v144
	v_permlane32_swap_b32_e32 v113, v161
	v_permlane32_swap_b32_e32 v129, v145
	v_permlane32_swap_b32_e32 v114, v162
	v_permlane32_swap_b32_e32 v130, v146
	v_permlane32_swap_b32_e32 v115, v163
	v_permlane32_swap_b32_e32 v131, v147
	v_permlane32_swap_b32_e32 v116, v164
	v_permlane32_swap_b32_e32 v132, v148
	v_permlane32_swap_b32_e32 v117, v165
	v_permlane32_swap_b32_e32 v133, v149
	v_permlane32_swap_b32_e32 v118, v166
	v_permlane32_swap_b32_e32 v134, v150
	v_permlane32_swap_b32_e32 v119, v167
	v_permlane32_swap_b32_e32 v135, v151
	s_waitcnt vmcnt(5)
	v_pk_mul_f32 v[76:77], v[74:75], v[70:71] op_sel:[0,1]
	s_nop 0
	v_pk_fma_f32 v[40:41], v[68:69], v[70:71], v[76:77] op_sel_hi:[1,0,1] neg_lo:[0,0,1]
	s_nop 0
	v_add_f32_e32 v70, v40, v104
	v_add_f32_e32 v71, v41, v120
	v_pk_mul_f32 v[76:77], v[74:75], v[70:71] op_sel:[0,1]
	v_cvt_pk_bf16_f32 v42, v70, v71
	v_pk_fma_f32 v[40:41], v[68:69], v[70:71], v[76:77] op_sel_hi:[1,0,1] neg_lo:[0,0,1]
	ds_write_b16 v103, v42
	v_add_f32_e32 v70, v40, v105
	v_add_f32_e32 v71, v41, v121
	ds_write_b16_d16_hi v103, v42 offset:128
	v_pk_mul_f32 v[76:77], v[74:75], v[70:71] op_sel:[0,1]
	v_cvt_pk_bf16_f32 v42, v70, v71
	v_pk_fma_f32 v[40:41], v[68:69], v[70:71], v[76:77] op_sel_hi:[1,0,1] neg_lo:[0,0,1]
	ds_write_b16 v103, v42 offset:272
	v_add_f32_e32 v70, v40, v106
	v_add_f32_e32 v71, v41, v122
	ds_write_b16_d16_hi v103, v42 offset:400
	v_pk_mul_f32 v[76:77], v[74:75], v[70:71] op_sel:[0,1]
	v_cvt_pk_bf16_f32 v42, v70, v71
	v_pk_fma_f32 v[40:41], v[68:69], v[70:71], v[76:77] op_sel_hi:[1,0,1] neg_lo:[0,0,1]
	ds_write_b16 v103, v42 offset:544
	v_add_f32_e32 v70, v40, v107
	v_add_f32_e32 v71, v41, v123
	ds_write_b16_d16_hi v103, v42 offset:672
	v_pk_mul_f32 v[76:77], v[74:75], v[70:71] op_sel:[0,1]
	v_cvt_pk_bf16_f32 v42, v70, v71
	v_pk_fma_f32 v[40:41], v[68:69], v[70:71], v[76:77] op_sel_hi:[1,0,1] neg_lo:[0,0,1]
	ds_write_b16 v103, v42 offset:816
	v_add_f32_e32 v70, v40, v152
	v_add_f32_e32 v71, v41, v136
	ds_write_b16_d16_hi v103, v42 offset:944
	v_pk_mul_f32 v[76:77], v[74:75], v[70:71] op_sel:[0,1]
	v_cvt_pk_bf16_f32 v42, v70, v71
	v_pk_fma_f32 v[40:41], v[68:69], v[70:71], v[76:77] op_sel_hi:[1,0,1] neg_lo:[0,0,1]
	ds_write_b16 v103, v42 offset:1088
	v_add_f32_e32 v70, v40, v153
	v_add_f32_e32 v71, v41, v137
	ds_write_b16_d16_hi v103, v42 offset:1216
	v_pk_mul_f32 v[76:77], v[74:75], v[70:71] op_sel:[0,1]
	v_cvt_pk_bf16_f32 v42, v70, v71
	v_pk_fma_f32 v[40:41], v[68:69], v[70:71], v[76:77] op_sel_hi:[1,0,1] neg_lo:[0,0,1]
	ds_write_b16 v103, v42 offset:1360
	v_add_f32_e32 v70, v40, v154
	v_add_f32_e32 v71, v41, v138
	ds_write_b16_d16_hi v103, v42 offset:1488
	v_pk_mul_f32 v[76:77], v[74:75], v[70:71] op_sel:[0,1]
; __device__ __forceinline__ bf f2bf(float f) { return (bf)(pk2(f, 0.f) & 0xFFFFu); }
; __device__ __forceinline__ void s5_pass2(const Params& p, int layer, int task, char* sm) {
;     ...
;       for (int l = 0; l < 32; l++) {
;         S5_STEP(sU + l * 16)
;         sS[l * 136 + lane] = f2bf(sr); sS[l * 136 + 64 + lane] = f2bf(si);
	v_cvt_pk_bf16_f32 v42, v70, v71
	v_pk_fma_f32 v[40:41], v[68:69], v[70:71], v[76:77] op_sel_hi:[1,0,1] neg_lo:[0,0,1]
	ds_write_b16 v103, v42 offset:1632
	v_add_f32_e32 v70, v40, v155
	v_add_f32_e32 v71, v41, v139
	ds_write_b16_d16_hi v103, v42 offset:1760
	v_pk_mul_f32 v[76:77], v[74:75], v[70:71] op_sel:[0,1]
	v_cvt_pk_bf16_f32 v42, v70, v71
	v_pk_fma_f32 v[40:41], v[68:69], v[70:71], v[76:77] op_sel_hi:[1,0,1] neg_lo:[0,0,1]
	ds_write_b16 v103, v42 offset:1904
	v_add_f32_e32 v70, v40, v108
	v_add_f32_e32 v71, v41, v124
	ds_write_b16_d16_hi v103, v42 offset:2032
	v_pk_mul_f32 v[76:77], v[74:75], v[70:71] op_sel:[0,1]
	v_cvt_pk_bf16_f32 v42, v70, v71
	v_pk_fma_f32 v[40:41], v[68:69], v[70:71], v[76:77] op_sel_hi:[1,0,1] neg_lo:[0,0,1]
	ds_write_b16 v103, v42 offset:2176
	v_add_f32_e32 v70, v40, v109
	v_add_f32_e32 v71, v41, v125
	ds_write_b16_d16_hi v103, v42 offset:2304
	v_pk_mul_f32 v[76:77], v[74:75], v[70:71] op_sel:[0,1]
	v_cvt_pk_bf16_f32 v42, v70, v71
	v_pk_fma_f32 v[40:41], v[68:69], v[70:71], v[76:77] op_sel_hi:[1,0,1] neg_lo:[0,0,1]
	ds_write_b16 v103, v42 offset:2448
	v_add_f32_e32 v70, v40, v110
	v_add_f32_e32 v71, v41, v126
	ds_write_b16_d16_hi v103, v42 offset:2576
	v_pk_mul_f32 v[76:77], v[74:75], v[70:71] op_sel:[0,1]
	v_cvt_pk_bf16_f32 v42, v70, v71
	v_pk_fma_f32 v[40:41], v[68:69], v[70:71], v[76:77] op_sel_hi:[1,0,1] neg_lo:[0,0,1]
	ds_write_b16 v103, v42 offset:2720
	v_add_f32_e32 v70, v40, v111
	v_add_f32_e32 v71, v41, v127
	ds_write_b16_d16_hi v103, v42 offset:2848
	v_pk_mul_f32 v[76:77], v[74:75], v[70:71] op_sel:[0,1]
	v_cvt_pk_bf16_f32 v42, v70, v71
	v_pk_fma_f32 v[40:41], v[68:69], v[70:71], v[76:77] op_sel_hi:[1,0,1] neg_lo:[0,0,1]
	ds_write_b16 v103, v42 offset:2992
	v_add_f32_e32 v70, v40, v156
	v_add_f32_e32 v71, v41, v140
	ds_write_b16_d16_hi v103, v42 offset:3120
	v_pk_mul_f32 v[76:77], v[74:75], v[70:71] op_sel:[0,1]
	v_cvt_pk_bf16_f32 v42, v70, v71
	v_pk_fma_f32 v[40:41], v[68:69], v[70:71], v[76:77] op_sel_hi:[1,0,1] neg_lo:[0,0,1]
	ds_write_b16 v103, v42 offset:3264
	v_add_f32_e32 v70, v40, v157
	v_add_f32_e32 v71, v41, v141
	ds_write_b16_d16_hi v103, v42 offset:3392
	v_pk_mul_f32 v[76:77], v[74:75], v[70:71] op_sel:[0,1]
	v_cvt_pk_bf16_f32 v42, v70, v71
	v_pk_fma_f32 v[40:41], v[68:69], v[70:71], v[76:77] op_sel_hi:[1,0,1] neg_lo:[0,0,1]
	ds_write_b16 v103, v42 offset:3536
	v_add_f32_e32 v70, v40, v158
	v_add_f32_e32 v71, v41, v142
	ds_write_b16_d16_hi v103, v42 offset:3664
	v_pk_mul_f32 v[76:77], v[74:75], v[70:71] op_sel:[0,1]
	v_cvt_pk_bf16_f32 v42, v70, v71
	v_pk_fma_f32 v[40:41], v[68:69], v[70:71], v[76:77] op_sel_hi:[1,0,1] neg_lo:[0,0,1]
	ds_write_b16 v103, v42 offset:3808
	v_add_f32_e32 v70, v40, v159
	v_add_f32_e32 v71, v41, v143
	ds_write_b16_d16_hi v103, v42 offset:3936
	v_pk_mul_f32 v[76:77], v[74:75], v[70:71] op_sel:[0,1]
	v_cvt_pk_bf16_f32 v42, v70, v71
	v_pk_fma_f32 v[40:41], v[68:69], v[70:71], v[76:77] op_sel_hi:[1,0,1] neg_lo:[0,0,1]
	ds_write_b16 v103, v42 offset:4080
	v_add_f32_e32 v70, v40, v112
	v_add_f32_e32 v71, v41, v128
	ds_write_b16_d16_hi v103, v42 offset:4208
	v_pk_mul_f32 v[76:77], v[74:75], v[70:71] op_sel:[0,1]
	v_cvt_pk_bf16_f32 v42, v70, v71
	v_pk_fma_f32 v[40:41], v[68:69], v[70:71], v[76:77] op_sel_hi:[1,0,1] neg_lo:[0,0,1]
	ds_write_b16 v103, v42 offset:4352
	v_add_f32_e32 v70, v40, v113
	v_add_f32_e32 v71, v41, v129
	ds_write_b16_d16_hi v103, v42 offset:4480
	v_pk_mul_f32 v[76:77], v[74:75], v[70:71] op_sel:[0,1]
	v_cvt_pk_bf16_f32 v42, v70, v71
	v_pk_fma_f32 v[40:41], v[68:69], v[70:71], v[76:77] op_sel_hi:[1,0,1] neg_lo:[0,0,1]
	ds_write_b16 v103, v42 offset:4624
	v_add_f32_e32 v70, v40, v114
	v_add_f32_e32 v71, v41, v130
	ds_write_b16_d16_hi v103, v42 offset:4752
	v_pk_mul_f32 v[76:77], v[74:75], v[70:71] op_sel:[0,1]
	v_cvt_pk_bf16_f32 v42, v70, v71
	v_pk_fma_f32 v[40:41], v[68:69], v[70:71], v[76:77] op_sel_hi:[1,0,1] neg_lo:[0,0,1]
	ds_write_b16 v103, v42 offset:4896
	v_add_f32_e32 v70, v40, v115
	v_add_f32_e32 v71, v41, v131
	ds_write_b16_d16_hi v103, v42 offset:5024
	v_pk_mul_f32 v[76:77], v[74:75], v[70:71] op_sel:[0,1]
	v_cvt_pk_bf16_f32 v42, v70, v71
	v_pk_fma_f32 v[40:41], v[68:69], v[70:71], v[76:77] op_sel_hi:[1,0,1] neg_lo:[0,0,1]
	ds_write_b16 v103, v42 offset:5168
	v_add_f32_e32 v70, v40, v160
	v_add_f32_e32 v71, v41, v144
	ds_write_b16_d16_hi v103, v42 offset:5296
	v_pk_mul_f32 v[76:77], v[74:75], v[70:71] op_sel:[0,1]
	v_cvt_pk_bf16_f32 v42, v70, v71
	v_pk_fma_f32 v[40:41], v[68:69], v[70:71], v[76:77] op_sel_hi:[1,0,1] neg_lo:[0,0,1]
	ds_write_b16 v103, v42 offset:5440
	v_add_f32_e32 v70, v40, v161
	v_add_f32_e32 v71, v41, v145
	ds_write_b16_d16_hi v103, v42 offset:5568
	v_pk_mul_f32 v[76:77], v[74:75], v[70:71] op_sel:[0,1]
	v_cvt_pk_bf16_f32 v42, v70, v71
	v_pk_fma_f32 v[40:41], v[68:69], v[70:71], v[76:77] op_sel_hi:[1,0,1] neg_lo:[0,0,1]
	ds_write_b16 v103, v42 offset:5712
	v_add_f32_e32 v70, v40, v162
	v_add_f32_e32 v71, v41, v146
	ds_write_b16_d16_hi v103, v42 offset:5840
	v_pk_mul_f32 v[76:77], v[74:75], v[70:71] op_sel:[0,1]
	v_cvt_pk_bf16_f32 v42, v70, v71
	v_pk_fma_f32 v[40:41], v[68:69], v[70:71], v[76:77] op_sel_hi:[1,0,1] neg_lo:[0,0,1]
	ds_write_b16 v103, v42 offset:5984
	v_add_f32_e32 v70, v40, v163
	v_add_f32_e32 v71, v41, v147
	ds_write_b16_d16_hi v103, v42 offset:6112
	v_pk_mul_f32 v[76:77], v[74:75], v[70:71] op_sel:[0,1]
	v_cvt_pk_bf16_f32 v42, v70, v71
	v_pk_fma_f32 v[40:41], v[68:69], v[70:71], v[76:77] op_sel_hi:[1,0,1] neg_lo:[0,0,1]
	ds_write_b16 v103, v42 offset:6256
	v_add_f32_e32 v70, v40, v116
	v_add_f32_e32 v71, v41, v132
	ds_write_b16_d16_hi v103, v42 offset:6384
	v_pk_mul_f32 v[76:77], v[74:75], v[70:71] op_sel:[0,1]
; __device__ __forceinline__ float ozero() { float z = 0.f; asm volatile("" : "+v"(z)); return z; }
; __device__ __forceinline__ bf f2bf(float f) { return (bf)(pk2(f, 0.f) & 0xFFFFu); }
; __device__ __forceinline__ f32x4 mfma16(bf16x8 a, bf16x8 b, f32x4 c) { return __builtin_amdgcn_mfma_f32_16x16x32_bf16(a, b, c, 0, 0, 0); }
; __device__ __forceinline__ void s5_pass2(const Params& p, int layer, int task, char* sm) {
;     ...
;       for (int l = 0; l < 32; l++) {
;         S5_STEP(sU + l * 16)
;         sS[l * 136 + lane] = f2bf(sr); sS[l * 136 + 64 + lane] = f2bf(si);
;       }
;       __builtin_amdgcn_wave_barrier();
; #pragma unroll
;       for (int mb = 0; mb < 2; mb++) {
;         const float z_ = ozero(); f32x4 acc = {z_, z_, z_, z_};
; #pragma unroll
;         for (int ks = 0; ks < 4; ks++) {
;           bf16x8 af = *(const bf16x8*)(sS + (16 * mb + (lane & 15)) * 136 + ks * 32 + 8 * (lane >> 4));
;           acc = mfma16(af, cf[ks], acc);
;         }
; #pragma unroll
;         for (int r = 0; r < 4; r++) {
;           const int l = 16 * mb + 4 * (lane >> 4) + r;
;           float y = acc[r] + dsk * sU[l * 16 + (lane & 15)];
;           p.YG[(tok0 + sub * 32 + l) * 512 + g * 16 + (lane & 15)] = f2bf(geluf_(y));
;         }
;       }
	v_cvt_pk_bf16_f32 v42, v70, v71
	v_pk_fma_f32 v[40:41], v[68:69], v[70:71], v[76:77] op_sel_hi:[1,0,1] neg_lo:[0,0,1]
	ds_write_b16 v103, v42 offset:6528
	v_add_f32_e32 v70, v40, v117
	v_add_f32_e32 v71, v41, v133
	ds_write_b16_d16_hi v103, v42 offset:6656
	v_pk_mul_f32 v[76:77], v[74:75], v[70:71] op_sel:[0,1]
	v_cvt_pk_bf16_f32 v42, v70, v71
	v_pk_fma_f32 v[40:41], v[68:69], v[70:71], v[76:77] op_sel_hi:[1,0,1] neg_lo:[0,0,1]
	ds_write_b16 v103, v42 offset:6800
	v_add_f32_e32 v70, v40, v118
	v_add_f32_e32 v71, v41, v134
	ds_write_b16_d16_hi v103, v42 offset:6928
	v_pk_mul_f32 v[76:77], v[74:75], v[70:71] op_sel:[0,1]
	v_cvt_pk_bf16_f32 v42, v70, v71
	v_pk_fma_f32 v[40:41], v[68:69], v[70:71], v[76:77] op_sel_hi:[1,0,1] neg_lo:[0,0,1]
	ds_write_b16 v103, v42 offset:7072
	v_add_f32_e32 v70, v40, v119
	v_add_f32_e32 v71, v41, v135
	ds_write_b16_d16_hi v103, v42 offset:7200
	v_pk_mul_f32 v[76:77], v[74:75], v[70:71] op_sel:[0,1]
	v_cvt_pk_bf16_f32 v42, v70, v71
	v_pk_fma_f32 v[40:41], v[68:69], v[70:71], v[76:77] op_sel_hi:[1,0,1] neg_lo:[0,0,1]
	ds_write_b16 v103, v42 offset:7344
	v_add_f32_e32 v70, v40, v164
	v_add_f32_e32 v71, v41, v148
	ds_write_b16_d16_hi v103, v42 offset:7472
	v_pk_mul_f32 v[76:77], v[74:75], v[70:71] op_sel:[0,1]
	v_cvt_pk_bf16_f32 v42, v70, v71
	v_pk_fma_f32 v[40:41], v[68:69], v[70:71], v[76:77] op_sel_hi:[1,0,1] neg_lo:[0,0,1]
	ds_write_b16 v103, v42 offset:7616
	v_add_f32_e32 v70, v40, v165
	v_add_f32_e32 v71, v41, v149
	ds_write_b16_d16_hi v103, v42 offset:7744
	v_pk_mul_f32 v[76:77], v[74:75], v[70:71] op_sel:[0,1]
	v_cvt_pk_bf16_f32 v42, v70, v71
	v_pk_fma_f32 v[40:41], v[68:69], v[70:71], v[76:77] op_sel_hi:[1,0,1] neg_lo:[0,0,1]
	ds_write_b16 v103, v42 offset:7888
	v_add_f32_e32 v70, v40, v166
	v_add_f32_e32 v71, v41, v150
	ds_write_b16_d16_hi v103, v42 offset:8016
	v_pk_mul_f32 v[76:77], v[74:75], v[70:71] op_sel:[0,1]
	v_cvt_pk_bf16_f32 v42, v70, v71
	v_pk_fma_f32 v[40:41], v[68:69], v[70:71], v[76:77] op_sel_hi:[1,0,1] neg_lo:[0,0,1]
	ds_write_b16 v103, v42 offset:8160
	v_add_f32_e32 v70, v40, v167
	v_add_f32_e32 v71, v41, v151
	ds_write_b16_d16_hi v103, v42 offset:8288
	v_cvt_pk_bf16_f32 v42, v70, v71
	ds_write_b16 v103, v42 offset:8432
	ds_write_b16_d16_hi v103, v42 offset:8560
	s_waitcnt lgkmcnt(0)
	v_mov_b32_e32 v145, 0
	v_mov_b32_e32 v40, v145
	ds_read_b128 v[104:107], v100 offset:2048
	ds_read_b32 v76, v83
	v_mov_b32_e32 v41, v40
	v_mov_b32_e32 v42, v40
	v_mov_b32_e32 v43, v40
	s_lshl_b32 s9, s11, 5
	v_mov_b32_e32 v77, s5
	s_cmp_eq_u32 s8, 4
	s_waitcnt vmcnt(4) lgkmcnt(1)
	v_mfma_f32_16x16x32_bf16 v[40:43], v[104:107], v[24:27], v[40:43]
	ds_read_b128 v[104:107], v100 offset:2112
	s_waitcnt vmcnt(3) lgkmcnt(0)
	v_mfma_f32_16x16x32_bf16 v[40:43], v[104:107], v[28:31], v[40:43]
	ds_read_b128 v[104:107], v100 offset:2176
	s_waitcnt vmcnt(2) lgkmcnt(0)
	v_mfma_f32_16x16x32_bf16 v[40:43], v[104:107], v[32:35], v[40:43]
	ds_read_b128 v[104:107], v100 offset:2240
	s_waitcnt vmcnt(1) lgkmcnt(0)
	v_mfma_f32_16x16x32_bf16 v[40:43], v[104:107], v[36:39], v[40:43]
	s_waitcnt vmcnt(0)
	s_nop 6
	v_fma_f32 v40, v102, v76, v40
	v_mul_f32_e32 v76, 0x3d372713, v40
	v_mul_f32_e32 v76, v40, v76
	v_fma_f32 v76, v40, v76, v40
	v_mul_f32_e32 v76, 0x3f4c422a, v76
	v_add_f32_e32 v76, v76, v76
	v_mul_f32_e32 v76, 0x3fb8aa3b, v76
	v_exp_f32_e32 v76, v76
	v_mul_f32_e32 v40, 0.5, v40
	v_add_f32_e32 v76, 1.0, v76
	v_rcp_f32_e32 v76, v76
	s_nop 0
	v_fma_f32 v76, v76, -2.0, 1.0
	v_add_f32_e32 v76, 1.0, v76
	v_mul_f32_e32 v40, v40, v76
	v_or_b32_e32 v76, s9, v82
	v_or_b32_e32 v76, s4, v76
	v_lshlrev_b64 v[104:105], 10, v[76:77]
	v_cvt_pk_bf16_f32 v40, v40, s0
	v_lshl_add_u64 v[104:105], v[72:73], 0, v[104:105]
	global_store_short v[104:105], v40, off
	ds_read_b32 v40, v85
	s_waitcnt lgkmcnt(0)
	v_fma_f32 v40, v102, v40, v41
	v_mul_f32_e32 v41, 0x3d372713, v40
	v_mul_f32_e32 v41, v40, v41
	v_fma_f32 v41, v40, v41, v40
	v_mul_f32_e32 v41, 0x3f4c422a, v41
	v_add_f32_e32 v41, v41, v41
	v_mul_f32_e32 v41, 0x3fb8aa3b, v41
	v_exp_f32_e32 v41, v41
	v_mul_f32_e32 v40, 0.5, v40
	v_add_f32_e32 v41, 1.0, v41
	v_rcp_f32_e32 v41, v41
	s_nop 0
	v_fma_f32 v41, v41, -2.0, 1.0
	v_add_f32_e32 v41, 1.0, v41
	v_mul_f32_e32 v40, v40, v41
	v_cvt_pk_bf16_f32 v103, v40, s0
	v_or_b32_e32 v40, s9, v84
	v_or_b32_e32 v76, s4, v40
	v_lshlrev_b64 v[40:41], 10, v[76:77]
	v_lshl_add_u64 v[40:41], v[72:73], 0, v[40:41]
	global_store_short v[40:41], v103, off
	ds_read_b32 v40, v87
	s_waitcnt lgkmcnt(0)
; __device__ __forceinline__ float ozero() { float z = 0.f; asm volatile("" : "+v"(z)); return z; }
; __device__ __forceinline__ bf f2bf(float f) { return (bf)(pk2(f, 0.f) & 0xFFFFu); }
; __device__ __forceinline__ f32x4 mfma16(bf16x8 a, bf16x8 b, f32x4 c) { return __builtin_amdgcn_mfma_f32_16x16x32_bf16(a, b, c, 0, 0, 0); }
; __device__ __forceinline__ float geluf_(float x) {
;   float u = 0.7978845608028654f * (x + 0.044715f * x * x * x);
;   float t = 1.f - 2.f * __builtin_amdgcn_rcpf(1.f + __expf(2.f * u));
;   return 0.5f * x * (1.f + t);
; }
; __device__ __forceinline__ void s5_pass2(const Params& p, int layer, int task, char* sm) {
;     ...
;       for (int mb = 0; mb < 2; mb++) {
;         const float z_ = ozero(); f32x4 acc = {z_, z_, z_, z_};
; #pragma unroll
;         for (int ks = 0; ks < 4; ks++) {
;           bf16x8 af = *(const bf16x8*)(sS + (16 * mb + (lane & 15)) * 136 + ks * 32 + 8 * (lane >> 4));
;           acc = mfma16(af, cf[ks], acc);
;         }
; #pragma unroll
;         for (int r = 0; r < 4; r++) {
;           const int l = 16 * mb + 4 * (lane >> 4) + r;
;           float y = acc[r] + dsk * sU[l * 16 + (lane & 15)];
;           p.YG[(tok0 + sub * 32 + l) * 512 + g * 16 + (lane & 15)] = f2bf(geluf_(y));
;         }
;       }
;     }
;   }
	v_fma_f32 v40, v102, v40, v42
	v_mul_f32_e32 v41, 0x3d372713, v40
	v_mul_f32_e32 v41, v40, v41
	v_fma_f32 v41, v40, v41, v40
	v_mul_f32_e32 v41, 0x3f4c422a, v41
	v_add_f32_e32 v41, v41, v41
	v_mul_f32_e32 v41, 0x3fb8aa3b, v41
	v_exp_f32_e32 v41, v41
	v_mul_f32_e32 v40, 0.5, v40
	v_add_f32_e32 v41, 1.0, v41
	v_rcp_f32_e32 v41, v41
	s_nop 0
	v_fma_f32 v41, v41, -2.0, 1.0
	v_add_f32_e32 v41, 1.0, v41
	v_mul_f32_e32 v40, v40, v41
	v_cvt_pk_bf16_f32 v42, v40, s0
	v_or_b32_e32 v40, s9, v86
	v_or_b32_e32 v76, s4, v40
	v_lshlrev_b64 v[40:41], 10, v[76:77]
	v_lshl_add_u64 v[40:41], v[72:73], 0, v[40:41]
	global_store_short v[40:41], v42, off
	ds_read_b32 v40, v89
	s_waitcnt lgkmcnt(0)
	v_fmac_f32_e32 v43, v102, v40
	v_mul_f32_e32 v40, 0x3d372713, v43
	v_mul_f32_e32 v40, v43, v40
	v_fma_f32 v40, v43, v40, v43
	v_mul_f32_e32 v40, 0x3f4c422a, v40
	v_add_f32_e32 v40, v40, v40
	v_mul_f32_e32 v40, 0x3fb8aa3b, v40
	v_exp_f32_e32 v40, v40
	v_mul_f32_e32 v41, 0.5, v43
	v_add_f32_e32 v40, 1.0, v40
	v_rcp_f32_e32 v40, v40
	s_nop 0
	v_fma_f32 v40, v40, -2.0, 1.0
	v_add_f32_e32 v40, 1.0, v40
	v_mul_f32_e32 v40, v41, v40
	v_cvt_pk_bf16_f32 v42, v40, s0
	v_or_b32_e32 v40, s9, v88
	v_or_b32_e32 v76, s4, v40
	v_lshlrev_b64 v[40:41], 10, v[76:77]
	v_lshl_add_u64 v[40:41], v[72:73], 0, v[40:41]
	global_store_short v[40:41], v42, off
	v_mov_b32_e32 v40, v145
	ds_read_b128 v[104:107], v100 offset:6400
	ds_read_b32 v76, v91
	v_mov_b32_e32 v41, v40
	v_mov_b32_e32 v42, v40
	v_mov_b32_e32 v43, v40
	s_waitcnt lgkmcnt(1)
	s_nop 0
	v_mfma_f32_16x16x32_bf16 v[40:43], v[104:107], v[24:27], v[40:43]
	ds_read_b128 v[104:107], v100 offset:6464
	s_waitcnt lgkmcnt(0)
	v_mfma_f32_16x16x32_bf16 v[40:43], v[104:107], v[28:31], v[40:43]
	ds_read_b128 v[104:107], v100 offset:6528
	s_waitcnt lgkmcnt(0)
	v_mfma_f32_16x16x32_bf16 v[40:43], v[104:107], v[32:35], v[40:43]
	ds_read_b128 v[104:107], v100 offset:6592
	s_waitcnt lgkmcnt(0)
	v_mfma_f32_16x16x32_bf16 v[40:43], v[104:107], v[36:39], v[40:43]
	s_nop 7
	v_fma_f32 v40, v102, v76, v40
	v_mul_f32_e32 v76, 0x3d372713, v40
	v_mul_f32_e32 v76, v40, v76
	v_fma_f32 v76, v40, v76, v40
	v_mul_f32_e32 v76, 0x3f4c422a, v76
	v_add_f32_e32 v76, v76, v76
	v_mul_f32_e32 v76, 0x3fb8aa3b, v76
	v_exp_f32_e32 v76, v76
	v_mul_f32_e32 v40, 0.5, v40
	v_add_f32_e32 v76, 1.0, v76
	v_rcp_f32_e32 v76, v76
	s_nop 0
	v_fma_f32 v76, v76, -2.0, 1.0
	v_add_f32_e32 v76, 1.0, v76
	v_mul_f32_e32 v40, v40, v76
	v_or_b32_e32 v76, s9, v90
	v_or_b32_e32 v76, s4, v76
	v_lshlrev_b64 v[104:105], 10, v[76:77]
	v_cvt_pk_bf16_f32 v40, v40, s0
	v_lshl_add_u64 v[104:105], v[72:73], 0, v[104:105]
	global_store_short v[104:105], v40, off
	ds_read_b32 v40, v93
	s_waitcnt lgkmcnt(0)
	v_fma_f32 v40, v102, v40, v41
	v_mul_f32_e32 v41, 0x3d372713, v40
	v_mul_f32_e32 v41, v40, v41
	v_fma_f32 v41, v40, v41, v40
	v_mul_f32_e32 v41, 0x3f4c422a, v41
	v_add_f32_e32 v41, v41, v41
	v_mul_f32_e32 v41, 0x3fb8aa3b, v41
	v_exp_f32_e32 v41, v41
	v_mul_f32_e32 v40, 0.5, v40
	v_add_f32_e32 v41, 1.0, v41
	v_rcp_f32_e32 v41, v41
	s_nop 0
	v_fma_f32 v41, v41, -2.0, 1.0
	v_add_f32_e32 v41, 1.0, v41
	v_mul_f32_e32 v40, v40, v41
	v_cvt_pk_bf16_f32 v103, v40, s0
	v_or_b32_e32 v40, s9, v92
	v_or_b32_e32 v76, s4, v40
	v_lshlrev_b64 v[40:41], 10, v[76:77]
	v_lshl_add_u64 v[40:41], v[72:73], 0, v[40:41]
	global_store_short v[40:41], v103, off
	ds_read_b32 v40, v95
	s_waitcnt lgkmcnt(0)
	v_fma_f32 v40, v102, v40, v42
	v_mul_f32_e32 v41, 0x3d372713, v40
	v_mul_f32_e32 v41, v40, v41
	v_fma_f32 v41, v40, v41, v40
	v_mul_f32_e32 v41, 0x3f4c422a, v41
	v_add_f32_e32 v41, v41, v41
	v_mul_f32_e32 v41, 0x3fb8aa3b, v41
	v_exp_f32_e32 v41, v41
	v_mul_f32_e32 v40, 0.5, v40
	v_add_f32_e32 v41, 1.0, v41
	v_rcp_f32_e32 v41, v41
	s_nop 0
	v_fma_f32 v41, v41, -2.0, 1.0
	v_add_f32_e32 v41, 1.0, v41
	v_mul_f32_e32 v40, v40, v41
	v_cvt_pk_bf16_f32 v42, v40, s0
	v_or_b32_e32 v40, s9, v94
	v_or_b32_e32 v76, s4, v40
	v_lshlrev_b64 v[40:41], 10, v[76:77]
	v_lshl_add_u64 v[40:41], v[72:73], 0, v[40:41]
	global_store_short v[40:41], v42, off
	ds_read_b32 v40, v97
	s_waitcnt lgkmcnt(0)
	v_fmac_f32_e32 v43, v102, v40
	v_mul_f32_e32 v40, 0x3d372713, v43
	v_mul_f32_e32 v40, v43, v40
	v_fma_f32 v40, v43, v40, v43
	v_mul_f32_e32 v40, 0x3f4c422a, v40
	v_add_f32_e32 v40, v40, v40
	v_mul_f32_e32 v40, 0x3fb8aa3b, v40
	v_exp_f32_e32 v40, v40
	v_mul_f32_e32 v41, 0.5, v43
	v_add_f32_e32 v40, 1.0, v40
	v_rcp_f32_e32 v40, v40
	s_nop 0
	v_fma_f32 v40, v40, -2.0, 1.0
	v_add_f32_e32 v40, 1.0, v40
	v_mul_f32_e32 v40, v41, v40
	v_cvt_pk_bf16_f32 v42, v40, s0
	v_or_b32_e32 v40, s9, v96
	v_or_b32_e32 v76, s4, v40
	v_lshlrev_b64 v[40:41], 10, v[76:77]
	v_lshl_add_u64 v[40:41], v[72:73], 0, v[40:41]
	global_store_short v[40:41], v42, off
	s_cbranch_scc1 .LBB0_1789
	s_mov_b32 s11, s8
	s_branch .LBB0_1791

; __device__ __forceinline__ void s5_pass2(const Params& p, int layer, int task, char* sm) {
;     ...
;     const int g = w * 8 + gi;
;     const size_t pi = ((size_t)(layer * 32 + g)) * 64 + lane;
;     f32x2 B2[16];
; #pragma unroll
;     for (int h = 0; h < 16; h++) { B2[h].x = p.SB[pi * 32 + h]; B2[h].y = p.SB[pi * 32 + 16 + h]; }
;     const float ar = p.SA[pi * 4], ai = p.SA[pi * 4 + 1];
;     float2 s0 = *(const float2*)(p.END + (((size_t)(b * 128 + c) * 32 + g) * 64 + lane) * 2);
;     float sr = s0.x, si = s0.y;
;     bf16x8 cf[4];
;     {
;       const bf* cm = p.CM + (((size_t)(layer * 32 + g)) * 16 + (lane & 15)) * 128 + 8 * (lane >> 4);
; #pragma unroll
;       for (int ks = 0; ks < 4; ks++) cf[ks] = *(const bf16x8*)(cm + ks * 32);
;     }
;     const float dsk = p.s5_d[(layer * 32 + g) * 16 + (lane & 15)];
.LBB0_2054:
	v_add_u32_e32 v101, s11, v80
	v_add_u32_e32 v144, s35, v101
	v_lshlrev_b64 v[40:41], 6, v[144:145]
	v_or_b32_e32 v40, v40, v44
	v_readlane_b32 s12, v253, 38
	v_lshlrev_b64 v[8:9], 7, v[40:41]
	v_readlane_b32 s16, v253, 42
	v_readlane_b32 s17, v253, 43
	v_readlane_b32 s18, v253, 44
	v_readlane_b32 s19, v253, 45
	v_lshl_add_u64 v[20:21], s[16:17], 0, v[8:9]
	global_load_dwordx4 v[24:27], v[20:21], off offset:48
	global_load_dwordx4 v[28:31], v[20:21], off offset:32
	global_load_dwordx4 v[32:35], v[20:21], off offset:16
	global_load_dwordx4 v[36:39], v[20:21], off
	global_load_dwordx4 v[8:11], v[20:21], off offset:112
	global_load_dwordx4 v[12:15], v[20:21], off offset:96
	global_load_dwordx4 v[16:19], v[20:21], off offset:80
	s_nop 0
	global_load_dwordx4 v[20:23], v[20:21], off offset:64
	v_readlane_b32 s13, v253, 39
	v_readlane_b32 s14, v253, 40
	v_readlane_b32 s15, v253, 41
	s_cmp_lg_u32 s11, 7
	s_cselect_b64 s[6:7], -1, 0
	s_xor_b64 s[6:7], s[6:7], -1
	s_waitcnt vmcnt(7)
	v_mov_b32_e32 v64, v24
	v_mov_b32_e32 v66, v26
	v_lshl_or_b32 v26, v101, 6, v50
	s_waitcnt vmcnt(4)
	v_mov_b32_e32 v52, v36
	s_waitcnt vmcnt(3)
	v_mov_b32_e32 v65, v8
	v_mov_b32_e32 v8, v25
	v_mov_b32_e32 v67, v10
	v_mov_b32_e32 v10, v27
	v_lshl_add_u64 v[24:25], v[40:41], 4, s[18:19]
	v_mov_b32_e32 v27, v45
	v_lshl_add_u64 v[26:27], v[26:27], 3, s[12:13]
	global_load_dwordx2 v[68:69], v[24:25], off
	global_load_dwordx2 v[70:71], v[26:27], off
	v_lshlrev_b64 v[24:25], 12, v[144:145]
	s_waitcnt vmcnt(2)
	v_mov_b32_e32 v53, v20
	v_mov_b32_e32 v20, v37
	v_lshl_add_u64 v[36:37], v[46:47], 0, v[24:25]
	v_mov_b32_e32 v54, v38
	v_mov_b32_e32 v55, v22
	v_mov_b32_e32 v22, v39
	v_mov_b32_e32 v56, v32
	v_mov_b32_e32 v57, v16
	v_mov_b32_e32 v16, v33
	v_mov_b32_e32 v58, v34
	v_mov_b32_e32 v59, v18
	v_mov_b32_e32 v18, v35
	v_mov_b32_e32 v60, v28
	v_mov_b32_e32 v61, v12
	v_mov_b32_e32 v12, v29
	v_mov_b32_e32 v62, v30
	v_mov_b32_e32 v63, v14
	v_mov_b32_e32 v14, v31
	global_load_dwordx4 v[24:27], v[36:37], off
	global_load_dwordx4 v[28:31], v[36:37], off offset:64
	global_load_dwordx4 v[32:35], v[36:37], off offset:128
	s_nop 0
	global_load_dwordx4 v[36:39], v[36:37], off offset:192
	v_readlane_b32 s12, v252, 16
	v_lshl_or_b32 v144, v144, 4, v81
	v_readlane_b32 s20, v252, 24
	v_readlane_b32 s21, v252, 25
	v_readlane_b32 s13, v252, 17
	v_readlane_b32 s14, v252, 18
	v_lshl_add_u64 v[40:41], v[144:145], 2, s[20:21]
	global_load_dword v102, v[40:41], off
	v_lshlrev_b32_e32 v144, 5, v101
	v_readlane_b32 s15, v252, 19
	v_readlane_b32 s16, v252, 20
	v_readlane_b32 s17, v252, 21
	v_readlane_b32 s18, v252, 22
	v_readlane_b32 s19, v252, 23
	v_readlane_b32 s22, v252, 26
	v_readlane_b32 s23, v252, 27
	v_readlane_b32 s24, v252, 28
	v_readlane_b32 s25, v252, 29
	v_readlane_b32 s26, v252, 30
	v_readlane_b32 s27, v252, 31
	v_lshl_add_u64 v[72:73], v[48:49], 0, v[144:145]
	s_mov_b32 s12, 0
	s_waitcnt vmcnt(6)
	v_pk_mov_b32 v[74:75], v[68:69], v[68:69] op_sel:[1,0]
	s_nop 1
	v_permlane32_swap_b32_e32 v52, v20
	v_permlane32_swap_b32_e32 v53, v21
	v_permlane32_swap_b32_e32 v54, v22
	v_permlane32_swap_b32_e32 v55, v23
	v_permlane32_swap_b32_e32 v56, v16
	v_permlane32_swap_b32_e32 v57, v17
	v_permlane32_swap_b32_e32 v58, v18
	v_permlane32_swap_b32_e32 v59, v19
	v_permlane32_swap_b32_e32 v60, v12
	v_permlane32_swap_b32_e32 v61, v13
	v_permlane32_swap_b32_e32 v62, v14
	v_permlane32_swap_b32_e32 v63, v15
	v_permlane32_swap_b32_e32 v64, v8
	v_permlane32_swap_b32_e32 v65, v9
	v_permlane32_swap_b32_e32 v66, v10
	v_permlane32_swap_b32_e32 v67, v11

; __device__ __forceinline__ bf f2bf(float f) { return (bf)(pk2(f, 0.f) & 0xFFFFu); }
; __device__ __forceinline__ void s5_pass2(const Params& p, int layer, int task, char* sm) {
;     ...
;     for (int sub = 0; sub < 4; sub++) {
;       __builtin_amdgcn_wave_barrier();
;       if (lane < 32) s5_st_u(sU + lane * 16, ua, ub);
;       {
;         const int nsub = (sub + 1) & 3; const int ng = g + (sub == 3 ? 1 : 0);
;         if (sub < 3 || gi < 7) s5_ld_u(p, tok0 + nsub * 32 + (lane & 31), ng, ua, ub);
;       }
;       __builtin_amdgcn_wave_barrier();
;       for (int l = 0; l < 32; l++) {
;         S5_STEP(sU + l * 16)
;         sS[l * 136 + lane] = f2bf(sr); sS[l * 136 + 64 + lane] = f2bf(si);
;       }
.LBB0_2060:
	v_add_u32_e32 v103, v79, v40
	v_and_b32_e32 v43, 31, v202
	v_lshrrev_b32_e32 v42, 5, v202
	v_lshlrev_b32_e32 v43, 6, v43
	v_lshl_add_u32 v43, v42, 2, v43
	v_add_u32_e32 v43, v79, v43
	ds_read2_b32 v[170:171], v43 offset0:0 offset1:2
	ds_read2_b32 v[172:173], v43 offset0:4 offset1:6
	ds_read2_b32 v[174:175], v43 offset0:8 offset1:10
	ds_read2_b32 v[176:177], v43 offset0:12 offset1:14
	s_waitcnt lgkmcnt(0)
	v_mfma_f32_32x32x2_f32 v[104:119], v170, v52, 0
	v_mfma_f32_32x32x2_f32 v[120:135], v170, v53, 0
	v_mfma_f32_32x32x2_f32 v[152:167], v170, v20, 0
	v_mfma_f32_32x32x2_f32 v[136:151], v170, v21, 0
	v_mfma_f32_32x32x2_f32 v[104:119], v171, v54, v[104:119]
	v_mfma_f32_32x32x2_f32 v[120:135], v171, v55, v[120:135]
	v_mfma_f32_32x32x2_f32 v[152:167], v171, v22, v[152:167]
	v_mfma_f32_32x32x2_f32 v[136:151], v171, v23, v[136:151]
	v_mfma_f32_32x32x2_f32 v[104:119], v172, v56, v[104:119]
	v_mfma_f32_32x32x2_f32 v[120:135], v172, v57, v[120:135]
	v_mfma_f32_32x32x2_f32 v[152:167], v172, v16, v[152:167]
	v_mfma_f32_32x32x2_f32 v[136:151], v172, v17, v[136:151]
	v_mfma_f32_32x32x2_f32 v[104:119], v173, v58, v[104:119]
	v_mfma_f32_32x32x2_f32 v[120:135], v173, v59, v[120:135]
	v_mfma_f32_32x32x2_f32 v[152:167], v173, v18, v[152:167]
	v_mfma_f32_32x32x2_f32 v[136:151], v173, v19, v[136:151]
	v_mfma_f32_32x32x2_f32 v[104:119], v174, v60, v[104:119]
	v_mfma_f32_32x32x2_f32 v[120:135], v174, v61, v[120:135]
	v_mfma_f32_32x32x2_f32 v[152:167], v174, v12, v[152:167]
	v_mfma_f32_32x32x2_f32 v[136:151], v174, v13, v[136:151]
	v_mfma_f32_32x32x2_f32 v[104:119], v175, v62, v[104:119]
	v_mfma_f32_32x32x2_f32 v[120:135], v175, v63, v[120:135]
	v_mfma_f32_32x32x2_f32 v[152:167], v175, v14, v[152:167]
	v_mfma_f32_32x32x2_f32 v[136:151], v175, v15, v[136:151]
	v_mfma_f32_32x32x2_f32 v[104:119], v176, v64, v[104:119]
	v_mfma_f32_32x32x2_f32 v[120:135], v176, v65, v[120:135]
	v_mfma_f32_32x32x2_f32 v[152:167], v176, v8, v[152:167]
	v_mfma_f32_32x32x2_f32 v[136:151], v176, v9, v[136:151]
	v_mfma_f32_32x32x2_f32 v[104:119], v177, v66, v[104:119]
	v_mfma_f32_32x32x2_f32 v[120:135], v177, v67, v[120:135]
	v_mfma_f32_32x32x2_f32 v[152:167], v177, v10, v[152:167]
	v_mfma_f32_32x32x2_f32 v[136:151], v177, v11, v[136:151]
	s_nop 7
	s_nop 7
	s_nop 7
	v_permlane32_swap_b32_e32 v104, v152
	v_permlane32_swap_b32_e32 v120, v136
	v_permlane32_swap_b32_e32 v105, v153
	v_permlane32_swap_b32_e32 v121, v137
	v_permlane32_swap_b32_e32 v106, v154
	v_permlane32_swap_b32_e32 v122, v138
	v_permlane32_swap_b32_e32 v107, v155
	v_permlane32_swap_b32_e32 v123, v139
	v_permlane32_swap_b32_e32 v108, v156
	v_permlane32_swap_b32_e32 v124, v140
	v_permlane32_swap_b32_e32 v109, v157
	v_permlane32_swap_b32_e32 v125, v141
	v_permlane32_swap_b32_e32 v110, v158
	v_permlane32_swap_b32_e32 v126, v142
	v_permlane32_swap_b32_e32 v111, v159
	v_permlane32_swap_b32_e32 v127, v143
	v_permlane32_swap_b32_e32 v112, v160
	v_permlane32_swap_b32_e32 v128, v144
	v_permlane32_swap_b32_e32 v113, v161
	v_permlane32_swap_b32_e32 v129, v145
	v_permlane32_swap_b32_e32 v114, v162
	v_permlane32_swap_b32_e32 v130, v146
	v_permlane32_swap_b32_e32 v115, v163
	v_permlane32_swap_b32_e32 v131, v147
	v_permlane32_swap_b32_e32 v116, v164
	v_permlane32_swap_b32_e32 v132, v148
	v_permlane32_swap_b32_e32 v117, v165
	v_permlane32_swap_b32_e32 v133, v149
	v_permlane32_swap_b32_e32 v118, v166
	v_permlane32_swap_b32_e32 v134, v150
	v_permlane32_swap_b32_e32 v119, v167
	v_permlane32_swap_b32_e32 v135, v151
	s_waitcnt vmcnt(5)
	v_pk_mul_f32 v[76:77], v[74:75], v[70:71] op_sel:[0,1]
	s_nop 0
	v_pk_fma_f32 v[40:41], v[68:69], v[70:71], v[76:77] op_sel_hi:[1,0,1] neg_lo:[0,0,1]
	s_nop 0
	v_add_f32_e32 v70, v40, v104
	v_add_f32_e32 v71, v41, v120
	v_pk_mul_f32 v[76:77], v[74:75], v[70:71] op_sel:[0,1]
	v_cvt_pk_bf16_f32 v42, v70, v71
	v_pk_fma_f32 v[40:41], v[68:69], v[70:71], v[76:77] op_sel_hi:[1,0,1] neg_lo:[0,0,1]
	ds_write_b16 v103, v42
	v_add_f32_e32 v70, v40, v105
	v_add_f32_e32 v71, v41, v121
	ds_write_b16_d16_hi v103, v42 offset:128
	v_pk_mul_f32 v[76:77], v[74:75], v[70:71] op_sel:[0,1]
	v_cvt_pk_bf16_f32 v42, v70, v71
	v_pk_fma_f32 v[40:41], v[68:69], v[70:71], v[76:77] op_sel_hi:[1,0,1] neg_lo:[0,0,1]
	ds_write_b16 v103, v42 offset:272
	v_add_f32_e32 v70, v40, v106
	v_add_f32_e32 v71, v41, v122
	ds_write_b16_d16_hi v103, v42 offset:400
	v_pk_mul_f32 v[76:77], v[74:75], v[70:71] op_sel:[0,1]
	v_cvt_pk_bf16_f32 v42, v70, v71
	v_pk_fma_f32 v[40:41], v[68:69], v[70:71], v[76:77] op_sel_hi:[1,0,1] neg_lo:[0,0,1]
	ds_write_b16 v103, v42 offset:544
	v_add_f32_e32 v70, v40, v107
	v_add_f32_e32 v71, v41, v123
	ds_write_b16_d16_hi v103, v42 offset:672
	v_pk_mul_f32 v[76:77], v[74:75], v[70:71] op_sel:[0,1]
	v_cvt_pk_bf16_f32 v42, v70, v71
	v_pk_fma_f32 v[40:41], v[68:69], v[70:71], v[76:77] op_sel_hi:[1,0,1] neg_lo:[0,0,1]
	ds_write_b16 v103, v42 offset:816
	v_add_f32_e32 v70, v40, v152
	v_add_f32_e32 v71, v41, v136
	ds_write_b16_d16_hi v103, v42 offset:944
	v_pk_mul_f32 v[76:77], v[74:75], v[70:71] op_sel:[0,1]
	v_cvt_pk_bf16_f32 v42, v70, v71
	v_pk_fma_f32 v[40:41], v[68:69], v[70:71], v[76:77] op_sel_hi:[1,0,1] neg_lo:[0,0,1]
	ds_write_b16 v103, v42 offset:1088
	v_add_f32_e32 v70, v40, v153
	v_add_f32_e32 v71, v41, v137
	ds_write_b16_d16_hi v103, v42 offset:1216
	v_pk_mul_f32 v[76:77], v[74:75], v[70:71] op_sel:[0,1]
	v_cvt_pk_bf16_f32 v42, v70, v71
	v_pk_fma_f32 v[40:41], v[68:69], v[70:71], v[76:77] op_sel_hi:[1,0,1] neg_lo:[0,0,1]
	ds_write_b16 v103, v42 offset:1360
	v_add_f32_e32 v70, v40, v154
	v_add_f32_e32 v71, v41, v138
	ds_write_b16_d16_hi v103, v42 offset:1488
	v_pk_mul_f32 v[76:77], v[74:75], v[70:71] op_sel:[0,1]
; __device__ __forceinline__ bf f2bf(float f) { return (bf)(pk2(f, 0.f) & 0xFFFFu); }
; __device__ __forceinline__ void s5_pass2(const Params& p, int layer, int task, char* sm) {
;     ...
;       for (int l = 0; l < 32; l++) {
;         S5_STEP(sU + l * 16)
;         sS[l * 136 + lane] = f2bf(sr); sS[l * 136 + 64 + lane] = f2bf(si);
	v_cvt_pk_bf16_f32 v42, v70, v71
	v_pk_fma_f32 v[40:41], v[68:69], v[70:71], v[76:77] op_sel_hi:[1,0,1] neg_lo:[0,0,1]
	ds_write_b16 v103, v42 offset:1632
	v_add_f32_e32 v70, v40, v155
	v_add_f32_e32 v71, v41, v139
	ds_write_b16_d16_hi v103, v42 offset:1760
	v_pk_mul_f32 v[76:77], v[74:75], v[70:71] op_sel:[0,1]
	v_cvt_pk_bf16_f32 v42, v70, v71
	v_pk_fma_f32 v[40:41], v[68:69], v[70:71], v[76:77] op_sel_hi:[1,0,1] neg_lo:[0,0,1]
	ds_write_b16 v103, v42 offset:1904
	v_add_f32_e32 v70, v40, v108
	v_add_f32_e32 v71, v41, v124
	ds_write_b16_d16_hi v103, v42 offset:2032
	v_pk_mul_f32 v[76:77], v[74:75], v[70:71] op_sel:[0,1]
	v_cvt_pk_bf16_f32 v42, v70, v71
	v_pk_fma_f32 v[40:41], v[68:69], v[70:71], v[76:77] op_sel_hi:[1,0,1] neg_lo:[0,0,1]
	ds_write_b16 v103, v42 offset:2176
	v_add_f32_e32 v70, v40, v109
	v_add_f32_e32 v71, v41, v125
	ds_write_b16_d16_hi v103, v42 offset:2304
	v_pk_mul_f32 v[76:77], v[74:75], v[70:71] op_sel:[0,1]
	v_cvt_pk_bf16_f32 v42, v70, v71
	v_pk_fma_f32 v[40:41], v[68:69], v[70:71], v[76:77] op_sel_hi:[1,0,1] neg_lo:[0,0,1]
	ds_write_b16 v103, v42 offset:2448
	v_add_f32_e32 v70, v40, v110
	v_add_f32_e32 v71, v41, v126
	ds_write_b16_d16_hi v103, v42 offset:2576
	v_pk_mul_f32 v[76:77], v[74:75], v[70:71] op_sel:[0,1]
	v_cvt_pk_bf16_f32 v42, v70, v71
	v_pk_fma_f32 v[40:41], v[68:69], v[70:71], v[76:77] op_sel_hi:[1,0,1] neg_lo:[0,0,1]
	ds_write_b16 v103, v42 offset:2720
	v_add_f32_e32 v70, v40, v111
	v_add_f32_e32 v71, v41, v127
	ds_write_b16_d16_hi v103, v42 offset:2848
	v_pk_mul_f32 v[76:77], v[74:75], v[70:71] op_sel:[0,1]
	v_cvt_pk_bf16_f32 v42, v70, v71
	v_pk_fma_f32 v[40:41], v[68:69], v[70:71], v[76:77] op_sel_hi:[1,0,1] neg_lo:[0,0,1]
	ds_write_b16 v103, v42 offset:2992
	v_add_f32_e32 v70, v40, v156
	v_add_f32_e32 v71, v41, v140
	ds_write_b16_d16_hi v103, v42 offset:3120
	v_pk_mul_f32 v[76:77], v[74:75], v[70:71] op_sel:[0,1]
	v_cvt_pk_bf16_f32 v42, v70, v71
	v_pk_fma_f32 v[40:41], v[68:69], v[70:71], v[76:77] op_sel_hi:[1,0,1] neg_lo:[0,0,1]
	ds_write_b16 v103, v42 offset:3264
	v_add_f32_e32 v70, v40, v157
	v_add_f32_e32 v71, v41, v141
	ds_write_b16_d16_hi v103, v42 offset:3392
	v_pk_mul_f32 v[76:77], v[74:75], v[70:71] op_sel:[0,1]
	v_cvt_pk_bf16_f32 v42, v70, v71
	v_pk_fma_f32 v[40:41], v[68:69], v[70:71], v[76:77] op_sel_hi:[1,0,1] neg_lo:[0,0,1]
	ds_write_b16 v103, v42 offset:3536
	v_add_f32_e32 v70, v40, v158
	v_add_f32_e32 v71, v41, v142
	ds_write_b16_d16_hi v103, v42 offset:3664
	v_pk_mul_f32 v[76:77], v[74:75], v[70:71] op_sel:[0,1]
	v_cvt_pk_bf16_f32 v42, v70, v71
	v_pk_fma_f32 v[40:41], v[68:69], v[70:71], v[76:77] op_sel_hi:[1,0,1] neg_lo:[0,0,1]
	ds_write_b16 v103, v42 offset:3808
	v_add_f32_e32 v70, v40, v159
	v_add_f32_e32 v71, v41, v143
	ds_write_b16_d16_hi v103, v42 offset:3936
	v_pk_mul_f32 v[76:77], v[74:75], v[70:71] op_sel:[0,1]
	v_cvt_pk_bf16_f32 v42, v70, v71
	v_pk_fma_f32 v[40:41], v[68:69], v[70:71], v[76:77] op_sel_hi:[1,0,1] neg_lo:[0,0,1]
	ds_write_b16 v103, v42 offset:4080
	v_add_f32_e32 v70, v40, v112
	v_add_f32_e32 v71, v41, v128
	ds_write_b16_d16_hi v103, v42 offset:4208
	v_pk_mul_f32 v[76:77], v[74:75], v[70:71] op_sel:[0,1]
	v_cvt_pk_bf16_f32 v42, v70, v71
	v_pk_fma_f32 v[40:41], v[68:69], v[70:71], v[76:77] op_sel_hi:[1,0,1] neg_lo:[0,0,1]
	ds_write_b16 v103, v42 offset:4352
	v_add_f32_e32 v70, v40, v113
	v_add_f32_e32 v71, v41, v129
	ds_write_b16_d16_hi v103, v42 offset:4480
	v_pk_mul_f32 v[76:77], v[74:75], v[70:71] op_sel:[0,1]
	v_cvt_pk_bf16_f32 v42, v70, v71
	v_pk_fma_f32 v[40:41], v[68:69], v[70:71], v[76:77] op_sel_hi:[1,0,1] neg_lo:[0,0,1]
	ds_write_b16 v103, v42 offset:4624
	v_add_f32_e32 v70, v40, v114
	v_add_f32_e32 v71, v41, v130
	ds_write_b16_d16_hi v103, v42 offset:4752
	v_pk_mul_f32 v[76:77], v[74:75], v[70:71] op_sel:[0,1]
	v_cvt_pk_bf16_f32 v42, v70, v71
	v_pk_fma_f32 v[40:41], v[68:69], v[70:71], v[76:77] op_sel_hi:[1,0,1] neg_lo:[0,0,1]
	ds_write_b16 v103, v42 offset:4896
	v_add_f32_e32 v70, v40, v115
	v_add_f32_e32 v71, v41, v131
	ds_write_b16_d16_hi v103, v42 offset:5024
	v_pk_mul_f32 v[76:77], v[74:75], v[70:71] op_sel:[0,1]
	v_cvt_pk_bf16_f32 v42, v70, v71
	v_pk_fma_f32 v[40:41], v[68:69], v[70:71], v[76:77] op_sel_hi:[1,0,1] neg_lo:[0,0,1]
	ds_write_b16 v103, v42 offset:5168
	v_add_f32_e32 v70, v40, v160
	v_add_f32_e32 v71, v41, v144
	ds_write_b16_d16_hi v103, v42 offset:5296
	v_pk_mul_f32 v[76:77], v[74:75], v[70:71] op_sel:[0,1]
	v_cvt_pk_bf16_f32 v42, v70, v71
	v_pk_fma_f32 v[40:41], v[68:69], v[70:71], v[76:77] op_sel_hi:[1,0,1] neg_lo:[0,0,1]
	ds_write_b16 v103, v42 offset:5440
	v_add_f32_e32 v70, v40, v161
	v_add_f32_e32 v71, v41, v145
	ds_write_b16_d16_hi v103, v42 offset:5568
	v_pk_mul_f32 v[76:77], v[74:75], v[70:71] op_sel:[0,1]
	v_cvt_pk_bf16_f32 v42, v70, v71
	v_pk_fma_f32 v[40:41], v[68:69], v[70:71], v[76:77] op_sel_hi:[1,0,1] neg_lo:[0,0,1]
	ds_write_b16 v103, v42 offset:5712
	v_add_f32_e32 v70, v40, v162
	v_add_f32_e32 v71, v41, v146
	ds_write_b16_d16_hi v103, v42 offset:5840
	v_pk_mul_f32 v[76:77], v[74:75], v[70:71] op_sel:[0,1]
	v_cvt_pk_bf16_f32 v42, v70, v71
	v_pk_fma_f32 v[40:41], v[68:69], v[70:71], v[76:77] op_sel_hi:[1,0,1] neg_lo:[0,0,1]
	ds_write_b16 v103, v42 offset:5984
	v_add_f32_e32 v70, v40, v163
	v_add_f32_e32 v71, v41, v147
	ds_write_b16_d16_hi v103, v42 offset:6112
	v_pk_mul_f32 v[76:77], v[74:75], v[70:71] op_sel:[0,1]
	v_cvt_pk_bf16_f32 v42, v70, v71
	v_pk_fma_f32 v[40:41], v[68:69], v[70:71], v[76:77] op_sel_hi:[1,0,1] neg_lo:[0,0,1]
	ds_write_b16 v103, v42 offset:6256
	v_add_f32_e32 v70, v40, v116
	v_add_f32_e32 v71, v41, v132
	ds_write_b16_d16_hi v103, v42 offset:6384
	v_pk_mul_f32 v[76:77], v[74:75], v[70:71] op_sel:[0,1]
; __device__ __forceinline__ float ozero() { float z = 0.f; asm volatile("" : "+v"(z)); return z; }
; __device__ __forceinline__ bf f2bf(float f) { return (bf)(pk2(f, 0.f) & 0xFFFFu); }
; __device__ __forceinline__ f32x4 mfma16(bf16x8 a, bf16x8 b, f32x4 c) { return __builtin_amdgcn_mfma_f32_16x16x32_bf16(a, b, c, 0, 0, 0); }
; __device__ __forceinline__ void s5_pass2(const Params& p, int layer, int task, char* sm) {
;     ...
;       for (int l = 0; l < 32; l++) {
;         S5_STEP(sU + l * 16)
;         sS[l * 136 + lane] = f2bf(sr); sS[l * 136 + 64 + lane] = f2bf(si);
;       }
;       __builtin_amdgcn_wave_barrier();
; #pragma unroll
;       for (int mb = 0; mb < 2; mb++) {
;         const float z_ = ozero(); f32x4 acc = {z_, z_, z_, z_};
; #pragma unroll
;         for (int ks = 0; ks < 4; ks++) {
;           bf16x8 af = *(const bf16x8*)(sS + (16 * mb + (lane & 15)) * 136 + ks * 32 + 8 * (lane >> 4));
;           acc = mfma16(af, cf[ks], acc);
;         }
; #pragma unroll
;         for (int r = 0; r < 4; r++) {
;           const int l = 16 * mb + 4 * (lane >> 4) + r;
;           float y = acc[r] + dsk * sU[l * 16 + (lane & 15)];
;           p.YG[(tok0 + sub * 32 + l) * 512 + g * 16 + (lane & 15)] = f2bf(geluf_(y));
;         }
;       }
	v_cvt_pk_bf16_f32 v42, v70, v71
	v_pk_fma_f32 v[40:41], v[68:69], v[70:71], v[76:77] op_sel_hi:[1,0,1] neg_lo:[0,0,1]
	ds_write_b16 v103, v42 offset:6528
	v_add_f32_e32 v70, v40, v117
	v_add_f32_e32 v71, v41, v133
	ds_write_b16_d16_hi v103, v42 offset:6656
	v_pk_mul_f32 v[76:77], v[74:75], v[70:71] op_sel:[0,1]
	v_cvt_pk_bf16_f32 v42, v70, v71
	v_pk_fma_f32 v[40:41], v[68:69], v[70:71], v[76:77] op_sel_hi:[1,0,1] neg_lo:[0,0,1]
	ds_write_b16 v103, v42 offset:6800
	v_add_f32_e32 v70, v40, v118
	v_add_f32_e32 v71, v41, v134
	ds_write_b16_d16_hi v103, v42 offset:6928
	v_pk_mul_f32 v[76:77], v[74:75], v[70:71] op_sel:[0,1]
	v_cvt_pk_bf16_f32 v42, v70, v71
	v_pk_fma_f32 v[40:41], v[68:69], v[70:71], v[76:77] op_sel_hi:[1,0,1] neg_lo:[0,0,1]
	ds_write_b16 v103, v42 offset:7072
	v_add_f32_e32 v70, v40, v119
	v_add_f32_e32 v71, v41, v135
	ds_write_b16_d16_hi v103, v42 offset:7200
	v_pk_mul_f32 v[76:77], v[74:75], v[70:71] op_sel:[0,1]
	v_cvt_pk_bf16_f32 v42, v70, v71
	v_pk_fma_f32 v[40:41], v[68:69], v[70:71], v[76:77] op_sel_hi:[1,0,1] neg_lo:[0,0,1]
	ds_write_b16 v103, v42 offset:7344
	v_add_f32_e32 v70, v40, v164
	v_add_f32_e32 v71, v41, v148
	ds_write_b16_d16_hi v103, v42 offset:7472
	v_pk_mul_f32 v[76:77], v[74:75], v[70:71] op_sel:[0,1]
	v_cvt_pk_bf16_f32 v42, v70, v71
	v_pk_fma_f32 v[40:41], v[68:69], v[70:71], v[76:77] op_sel_hi:[1,0,1] neg_lo:[0,0,1]
	ds_write_b16 v103, v42 offset:7616
	v_add_f32_e32 v70, v40, v165
	v_add_f32_e32 v71, v41, v149
	ds_write_b16_d16_hi v103, v42 offset:7744
	v_pk_mul_f32 v[76:77], v[74:75], v[70:71] op_sel:[0,1]
	v_cvt_pk_bf16_f32 v42, v70, v71
	v_pk_fma_f32 v[40:41], v[68:69], v[70:71], v[76:77] op_sel_hi:[1,0,1] neg_lo:[0,0,1]
	ds_write_b16 v103, v42 offset:7888
	v_add_f32_e32 v70, v40, v166
	v_add_f32_e32 v71, v41, v150
	ds_write_b16_d16_hi v103, v42 offset:8016
	v_pk_mul_f32 v[76:77], v[74:75], v[70:71] op_sel:[0,1]
	v_cvt_pk_bf16_f32 v42, v70, v71
	v_pk_fma_f32 v[40:41], v[68:69], v[70:71], v[76:77] op_sel_hi:[1,0,1] neg_lo:[0,0,1]
	ds_write_b16 v103, v42 offset:8160
	v_add_f32_e32 v70, v40, v167
	v_add_f32_e32 v71, v41, v151
	ds_write_b16_d16_hi v103, v42 offset:8288
	v_cvt_pk_bf16_f32 v42, v70, v71
	ds_write_b16 v103, v42 offset:8432
	ds_write_b16_d16_hi v103, v42 offset:8560
	s_waitcnt lgkmcnt(0)
	v_mov_b32_e32 v145, 0
	v_mov_b32_e32 v40, v145
	ds_read_b128 v[104:107], v100 offset:2048
	ds_read_b32 v76, v83
	v_mov_b32_e32 v41, v40
	v_mov_b32_e32 v42, v40
	v_mov_b32_e32 v43, v40
	s_lshl_b32 s9, s12, 5
	v_mov_b32_e32 v77, s5
	s_cmp_eq_u32 s8, 4
	s_waitcnt vmcnt(4) lgkmcnt(1)
	v_mfma_f32_16x16x32_bf16 v[40:43], v[104:107], v[24:27], v[40:43]
	ds_read_b128 v[104:107], v100 offset:2112
	s_waitcnt vmcnt(3) lgkmcnt(0)
	v_mfma_f32_16x16x32_bf16 v[40:43], v[104:107], v[28:31], v[40:43]
	ds_read_b128 v[104:107], v100 offset:2176
	s_waitcnt vmcnt(2) lgkmcnt(0)
	v_mfma_f32_16x16x32_bf16 v[40:43], v[104:107], v[32:35], v[40:43]
	ds_read_b128 v[104:107], v100 offset:2240
	s_waitcnt vmcnt(1) lgkmcnt(0)
	v_mfma_f32_16x16x32_bf16 v[40:43], v[104:107], v[36:39], v[40:43]
	s_waitcnt vmcnt(0)
	s_nop 6
	v_fma_f32 v40, v102, v76, v40
	v_mul_f32_e32 v76, 0x3d372713, v40
	v_mul_f32_e32 v76, v40, v76
	v_fma_f32 v76, v40, v76, v40
	v_mul_f32_e32 v76, 0x3f4c422a, v76
	v_add_f32_e32 v76, v76, v76
	v_mul_f32_e32 v76, 0x3fb8aa3b, v76
	v_exp_f32_e32 v76, v76
	v_mul_f32_e32 v40, 0.5, v40
	v_add_f32_e32 v76, 1.0, v76
	v_rcp_f32_e32 v76, v76
	s_nop 0
	v_fma_f32 v76, v76, -2.0, 1.0
	v_add_f32_e32 v76, 1.0, v76
	v_mul_f32_e32 v40, v40, v76
	v_or_b32_e32 v76, s9, v82
	v_or_b32_e32 v76, s4, v76
	v_lshlrev_b64 v[104:105], 10, v[76:77]
	v_cvt_pk_bf16_f32 v40, v40, s0
	v_lshl_add_u64 v[104:105], v[72:73], 0, v[104:105]
	global_store_short v[104:105], v40, off
	ds_read_b32 v40, v85
	s_waitcnt lgkmcnt(0)
	v_fma_f32 v40, v102, v40, v41
	v_mul_f32_e32 v41, 0x3d372713, v40
	v_mul_f32_e32 v41, v40, v41
	v_fma_f32 v41, v40, v41, v40
	v_mul_f32_e32 v41, 0x3f4c422a, v41
	v_add_f32_e32 v41, v41, v41
	v_mul_f32_e32 v41, 0x3fb8aa3b, v41
	v_exp_f32_e32 v41, v41
	v_mul_f32_e32 v40, 0.5, v40
	v_add_f32_e32 v41, 1.0, v41
	v_rcp_f32_e32 v41, v41
	s_nop 0
	v_fma_f32 v41, v41, -2.0, 1.0
	v_add_f32_e32 v41, 1.0, v41
	v_mul_f32_e32 v40, v40, v41
	v_cvt_pk_bf16_f32 v103, v40, s0
	v_or_b32_e32 v40, s9, v84
	v_or_b32_e32 v76, s4, v40
	v_lshlrev_b64 v[40:41], 10, v[76:77]
	v_lshl_add_u64 v[40:41], v[72:73], 0, v[40:41]
	global_store_short v[40:41], v103, off
	ds_read_b32 v40, v87
	s_waitcnt lgkmcnt(0)
; __device__ __forceinline__ float ozero() { float z = 0.f; asm volatile("" : "+v"(z)); return z; }
; __device__ __forceinline__ bf f2bf(float f) { return (bf)(pk2(f, 0.f) & 0xFFFFu); }
; __device__ __forceinline__ f32x4 mfma16(bf16x8 a, bf16x8 b, f32x4 c) { return __builtin_amdgcn_mfma_f32_16x16x32_bf16(a, b, c, 0, 0, 0); }
; __device__ __forceinline__ float geluf_(float x) {
;   float u = 0.7978845608028654f * (x + 0.044715f * x * x * x);
;   float t = 1.f - 2.f * __builtin_amdgcn_rcpf(1.f + __expf(2.f * u));
;   return 0.5f * x * (1.f + t);
; }
; __device__ __forceinline__ void s5_pass2(const Params& p, int layer, int task, char* sm) {
;     ...
;       for (int mb = 0; mb < 2; mb++) {
;         const float z_ = ozero(); f32x4 acc = {z_, z_, z_, z_};
; #pragma unroll
;         for (int ks = 0; ks < 4; ks++) {
;           bf16x8 af = *(const bf16x8*)(sS + (16 * mb + (lane & 15)) * 136 + ks * 32 + 8 * (lane >> 4));
;           acc = mfma16(af, cf[ks], acc);
;         }
; #pragma unroll
;         for (int r = 0; r < 4; r++) {
;           const int l = 16 * mb + 4 * (lane >> 4) + r;
;           float y = acc[r] + dsk * sU[l * 16 + (lane & 15)];
;           p.YG[(tok0 + sub * 32 + l) * 512 + g * 16 + (lane & 15)] = f2bf(geluf_(y));
;         }
;       }
;     }
;   }
	v_fma_f32 v40, v102, v40, v42
	v_mul_f32_e32 v41, 0x3d372713, v40
	v_mul_f32_e32 v41, v40, v41
	v_fma_f32 v41, v40, v41, v40
	v_mul_f32_e32 v41, 0x3f4c422a, v41
	v_add_f32_e32 v41, v41, v41
	v_mul_f32_e32 v41, 0x3fb8aa3b, v41
	v_exp_f32_e32 v41, v41
	v_mul_f32_e32 v40, 0.5, v40
	v_add_f32_e32 v41, 1.0, v41
	v_rcp_f32_e32 v41, v41
	s_nop 0
	v_fma_f32 v41, v41, -2.0, 1.0
	v_add_f32_e32 v41, 1.0, v41
	v_mul_f32_e32 v40, v40, v41
	v_cvt_pk_bf16_f32 v42, v40, s0
	v_or_b32_e32 v40, s9, v86
	v_or_b32_e32 v76, s4, v40
	v_lshlrev_b64 v[40:41], 10, v[76:77]
	v_lshl_add_u64 v[40:41], v[72:73], 0, v[40:41]
	global_store_short v[40:41], v42, off
	ds_read_b32 v40, v89
	s_waitcnt lgkmcnt(0)
	v_fmac_f32_e32 v43, v102, v40
	v_mul_f32_e32 v40, 0x3d372713, v43
	v_mul_f32_e32 v40, v43, v40
	v_fma_f32 v40, v43, v40, v43
	v_mul_f32_e32 v40, 0x3f4c422a, v40
	v_add_f32_e32 v40, v40, v40
	v_mul_f32_e32 v40, 0x3fb8aa3b, v40
	v_exp_f32_e32 v40, v40
	v_mul_f32_e32 v41, 0.5, v43
	v_add_f32_e32 v40, 1.0, v40
	v_rcp_f32_e32 v40, v40
	s_nop 0
	v_fma_f32 v40, v40, -2.0, 1.0
	v_add_f32_e32 v40, 1.0, v40
	v_mul_f32_e32 v40, v41, v40
	v_cvt_pk_bf16_f32 v42, v40, s0
	v_or_b32_e32 v40, s9, v88
	v_or_b32_e32 v76, s4, v40
	v_lshlrev_b64 v[40:41], 10, v[76:77]
	v_lshl_add_u64 v[40:41], v[72:73], 0, v[40:41]
	global_store_short v[40:41], v42, off
	v_mov_b32_e32 v40, v145
	ds_read_b128 v[104:107], v100 offset:6400
	ds_read_b32 v76, v91
	v_mov_b32_e32 v41, v40
	v_mov_b32_e32 v42, v40
	v_mov_b32_e32 v43, v40
	s_waitcnt lgkmcnt(1)
	s_nop 0
	v_mfma_f32_16x16x32_bf16 v[40:43], v[104:107], v[24:27], v[40:43]
	ds_read_b128 v[104:107], v100 offset:6464
	s_waitcnt lgkmcnt(0)
	v_mfma_f32_16x16x32_bf16 v[40:43], v[104:107], v[28:31], v[40:43]
	ds_read_b128 v[104:107], v100 offset:6528
	s_waitcnt lgkmcnt(0)
	v_mfma_f32_16x16x32_bf16 v[40:43], v[104:107], v[32:35], v[40:43]
	ds_read_b128 v[104:107], v100 offset:6592
	s_waitcnt lgkmcnt(0)
	v_mfma_f32_16x16x32_bf16 v[40:43], v[104:107], v[36:39], v[40:43]
	s_nop 7
	v_fma_f32 v40, v102, v76, v40
	v_mul_f32_e32 v76, 0x3d372713, v40
	v_mul_f32_e32 v76, v40, v76
	v_fma_f32 v76, v40, v76, v40
	v_mul_f32_e32 v76, 0x3f4c422a, v76
	v_add_f32_e32 v76, v76, v76
	v_mul_f32_e32 v76, 0x3fb8aa3b, v76
	v_exp_f32_e32 v76, v76
	v_mul_f32_e32 v40, 0.5, v40
	v_add_f32_e32 v76, 1.0, v76
	v_rcp_f32_e32 v76, v76
	s_nop 0
	v_fma_f32 v76, v76, -2.0, 1.0
	v_add_f32_e32 v76, 1.0, v76
	v_mul_f32_e32 v40, v40, v76
	v_or_b32_e32 v76, s9, v90
	v_or_b32_e32 v76, s4, v76
	v_lshlrev_b64 v[104:105], 10, v[76:77]
	v_cvt_pk_bf16_f32 v40, v40, s0
	v_lshl_add_u64 v[104:105], v[72:73], 0, v[104:105]
	global_store_short v[104:105], v40, off
	ds_read_b32 v40, v93
	s_waitcnt lgkmcnt(0)
	v_fma_f32 v40, v102, v40, v41
	v_mul_f32_e32 v41, 0x3d372713, v40
	v_mul_f32_e32 v41, v40, v41
	v_fma_f32 v41, v40, v41, v40
	v_mul_f32_e32 v41, 0x3f4c422a, v41
	v_add_f32_e32 v41, v41, v41
	v_mul_f32_e32 v41, 0x3fb8aa3b, v41
	v_exp_f32_e32 v41, v41
	v_mul_f32_e32 v40, 0.5, v40
	v_add_f32_e32 v41, 1.0, v41
	v_rcp_f32_e32 v41, v41
	s_nop 0
	v_fma_f32 v41, v41, -2.0, 1.0
	v_add_f32_e32 v41, 1.0, v41
	v_mul_f32_e32 v40, v40, v41
	v_cvt_pk_bf16_f32 v103, v40, s0
	v_or_b32_e32 v40, s9, v92
	v_or_b32_e32 v76, s4, v40
	v_lshlrev_b64 v[40:41], 10, v[76:77]
	v_lshl_add_u64 v[40:41], v[72:73], 0, v[40:41]
	global_store_short v[40:41], v103, off
	ds_read_b32 v40, v95
	s_waitcnt lgkmcnt(0)
	v_fma_f32 v40, v102, v40, v42
	v_mul_f32_e32 v41, 0x3d372713, v40
	v_mul_f32_e32 v41, v40, v41
	v_fma_f32 v41, v40, v41, v40
	v_mul_f32_e32 v41, 0x3f4c422a, v41
	v_add_f32_e32 v41, v41, v41
	v_mul_f32_e32 v41, 0x3fb8aa3b, v41
	v_exp_f32_e32 v41, v41
	v_mul_f32_e32 v40, 0.5, v40
	v_add_f32_e32 v41, 1.0, v41
	v_rcp_f32_e32 v41, v41
	s_nop 0
	v_fma_f32 v41, v41, -2.0, 1.0
	v_add_f32_e32 v41, 1.0, v41
	v_mul_f32_e32 v40, v40, v41
	v_cvt_pk_bf16_f32 v42, v40, s0
	v_or_b32_e32 v40, s9, v94
	v_or_b32_e32 v76, s4, v40
	v_lshlrev_b64 v[40:41], 10, v[76:77]
	v_lshl_add_u64 v[40:41], v[72:73], 0, v[40:41]
	global_store_short v[40:41], v42, off
	ds_read_b32 v40, v97
	s_waitcnt lgkmcnt(0)
	v_fmac_f32_e32 v43, v102, v40
	v_mul_f32_e32 v40, 0x3d372713, v43
	v_mul_f32_e32 v40, v43, v40
	v_fma_f32 v40, v43, v40, v43
	v_mul_f32_e32 v40, 0x3f4c422a, v40
	v_add_f32_e32 v40, v40, v40
	v_mul_f32_e32 v40, 0x3fb8aa3b, v40
	v_exp_f32_e32 v40, v40
	v_mul_f32_e32 v41, 0.5, v43
	v_add_f32_e32 v40, 1.0, v40
	v_rcp_f32_e32 v40, v40
	s_nop 0
	v_fma_f32 v40, v40, -2.0, 1.0
	v_add_f32_e32 v40, 1.0, v40
	v_mul_f32_e32 v40, v41, v40
	v_cvt_pk_bf16_f32 v42, v40, s0
	v_or_b32_e32 v40, s9, v96
	v_or_b32_e32 v76, s4, v40
	v_lshlrev_b64 v[40:41], 10, v[76:77]
	v_lshl_add_u64 v[40:41], v[72:73], 0, v[40:41]
	global_store_short v[40:41], v42, off
	s_cbranch_scc1 .LBB0_2053
	s_mov_b32 s12, s8
	s_branch .LBB0_2055
